# v11 + prompt attention: all four Q fragments kept in v210-v225 for the whole unit (per-step Q ds_reads removed), step-head wait lgkmcnt(2)
# baseline (speedup 1.0000x reference)
.LBB0_1066:
	s_and_b32 s0, s66, 0x3fffffc0
	s_lshl_b32 s0, s0, 2
	s_add_i32 s85, s0, 0
	s_add_i32 s5, s5, 3
	s_add_i32 s85, s85, 0x18000
	s_and_b32 s0, s5, -2
	s_cmp_gt_i32 s4, 1
	s_cselect_b32 s86, s0, 4
	s_lshl_b32 s0, s67, 13
	s_add_i32 s0, s0, 0
	v_lshlrev_b32_e32 v2, 10, v236
	v_lshlrev_b32_e32 v20, 4, v235
	v_add3_u32 v247, s0, v2, v20
	s_waitcnt vmcnt(6) lgkmcnt(0)
	s_barrier
	ds_read_b128 v[54:57], v247
	ds_read_b128 v[58:61], v247 offset:512
	s_waitcnt lgkmcnt(1)
	v_mfma_f32_32x32x16_bf16 v[20:35], v[54:57], v[48:51], v[4:19]
	v_lshlrev_b32_e32 v2, 1, v52
	v_and_b32_e32 v241, 32, v2
	v_lshlrev_b32_e32 v2, 4, v52
	v_and_b32_e32 v2, 0xc0, v2
	v_lshl_or_b32 v240, v236, 8, v2
	v_add_u32_e32 v2, 0, v241
	v_add3_u32 v246, v2, v239, v240
	s_waitcnt lgkmcnt(0)
	v_mfma_f32_32x32x16_bf16 v[4:19], v[58:61], v[48:51], v[4:19]
	ds_read_b128 v[48:51], v247 offset:2048
	ds_read_b128 v[54:57], v247 offset:2560
	s_min_i32 s0, s91, 3
	s_ashr_i32 s1, s0, 31
	s_lshl_b64 s[0:1], s[0:1], 17
	s_add_u32 s0, s87, s0
	s_addc_u32 s1, s88, s1
	s_mov_b32 s93, 1
	s_waitcnt lgkmcnt(1)
	v_mfma_f32_32x32x16_bf16 v[20:35], v[48:51], v[44:47], v[20:35]
	s_mov_b32 s34, 0
	v_lshl_add_u32 v242, v235, 2, s85
	s_waitcnt lgkmcnt(0)
	v_mfma_f32_32x32x16_bf16 v[4:19], v[54:57], v[44:47], v[4:19]
	ds_read_b128 v[44:47], v247 offset:4096
	ds_read_b128 v[48:51], v247 offset:4608
	s_waitcnt lgkmcnt(1)
	v_mfma_f32_32x32x16_bf16 v[20:35], v[44:47], v[40:43], v[20:35]
	s_waitcnt lgkmcnt(0)
	v_mfma_f32_32x32x16_bf16 v[4:19], v[48:51], v[40:43], v[4:19]
	ds_read_b128 v[40:43], v247 offset:6144
	ds_read_b128 v[44:47], v247 offset:6656
	s_waitcnt lgkmcnt(1)
	v_mfma_f32_32x32x16_bf16 v[20:35], v[40:43], v[36:39], v[20:35]
	s_waitcnt lgkmcnt(0)
	v_mfma_f32_32x32x16_bf16 v[4:19], v[44:47], v[36:39], v[4:19]
	s_nop 15
	s_nop 7
	s_nop 0
	v_max3_f32 v2, v20, v21, v4
	v_max3_f32 v36, v22, v23, v5
	s_nop 0
	v_max3_f32 v2, v2, v6, v7
	v_max3_f32 v36, v36, v26, v27
	s_nop 0
	v_max3_f32 v2, v2, v24, v25
	v_max3_f32 v36, v36, v10, v11
	s_nop 0
	v_max3_f32 v2, v2, v8, v9
	v_max3_f32 v36, v36, v30, v31
	s_nop 0
	v_max3_f32 v2, v2, v28, v29
	v_max3_f32 v36, v36, v14, v15
	s_nop 0
	v_max3_f32 v2, v2, v12, v13
	v_max3_f32 v36, v36, v34, v35
	s_nop 0
	v_max3_f32 v2, v2, v32, v33
	v_max3_f32 v36, v36, v18, v19
	s_nop 0
	v_max3_f32 v2, v2, v16, v17
	s_nop 0
	v_max_f32_e32 v2, v2, v36
	s_nop 0
	v_mov_b32_e32 v36, v2
	s_nop 1
	v_permlane32_swap_b32_e32 v2, v36
	v_max_f32_e32 v2, v2, v36
	s_nop 0
	v_add_f32_e32 v245, v3, v2
	v_sub_f32_e32 v20, v20, v2
	v_sub_f32_e32 v4, v4, v2
	v_sub_f32_e32 v21, v21, v2
	v_sub_f32_e32 v5, v5, v2
	v_sub_f32_e32 v22, v22, v2
	s_nop 0
	v_xor_b32_e32 v82, 0x80000000, v245
	v_mov_b32_e32 v83, v82
	v_mov_b32_e32 v84, v82
	v_mov_b32_e32 v85, v82
	v_mov_b32_e32 v86, v82
	v_mov_b32_e32 v87, v82
	v_mov_b32_e32 v88, v82
	v_mov_b32_e32 v89, v82
	v_mov_b32_e32 v90, v82
	v_mov_b32_e32 v91, v82
	v_mov_b32_e32 v92, v82
	v_mov_b32_e32 v93, v82
	v_mov_b32_e32 v94, v82
	v_mov_b32_e32 v95, v82
	v_mov_b32_e32 v96, v82
	v_mov_b32_e32 v97, v82
	s_waitcnt vmcnt(0) lgkmcnt(0)
	s_barrier
	s_mov_b32 s2, m0
	s_mov_b32 m0, s81
	s_nop 4
	global_load_lds_dwordx4 v237, s[0:1]
	s_mov_b32 m0, s2
	s_add_u32 s0, s0, 0x80
	s_addc_u32 s1, s1, 0
	s_cmp_lg_u32 0, -1
	s_cselect_b32 s2, 0, 0
	s_add_i32 s2, s2, s79
	s_add_i32 s82, s2, 0x2000
	s_mov_b32 s3, m0
	s_mov_b32 m0, s82
	s_nop 4
	global_load_lds_dwordx4 v237, s[0:1]
	s_mov_b32 m0, s3
	s_min_i32 s0, s91, 1
	s_ashr_i32 s1, s0, 31
	s_lshl_b64 s[0:1], s[0:1], 17
	s_add_u32 s0, s89, s0
	s_addc_u32 s1, s90, s1
	s_add_i32 s3, s2, 0x10000
	s_mov_b32 s4, m0
	s_mov_b32 m0, s3
	s_nop 4
	global_load_lds_dwordx4 v238, s[0:1]
	s_mov_b32 m0, s4
	s_add_u32 s0, s0, 0x80
	s_addc_u32 s1, s1, 0
	s_add_i32 s84, s2, 0xe000
	s_add_i32 s2, s2, 0x12000
	s_mov_b32 s3, m0
	s_mov_b32 m0, s2
	s_nop 4
	global_load_lds_dwordx4 v238, s[0:1]
	s_mov_b32 m0, s3
	ds_read_b128 v[206:209], v247 offset:16384
	ds_read_b128 v[202:205], v247 offset:16896
	ds_read_b128 v[198:201], v247 offset:18432
	ds_read_b128 v[194:197], v247 offset:18944
	ds_read_b128 v[190:193], v247 offset:20480
	ds_read_b128 v[186:189], v247 offset:20992
	ds_read_b128 v[182:185], v247 offset:22528
	ds_read_b128 v[178:181], v247 offset:23040
	v_sub_f32_e32 v6, v6, v2
	v_sub_f32_e32 v23, v23, v2
	v_sub_f32_e32 v7, v7, v2
	v_sub_f32_e32 v24, v24, v2
	v_sub_f32_e32 v8, v8, v2
	v_sub_f32_e32 v25, v25, v2
	v_sub_f32_e32 v9, v9, v2
	v_sub_f32_e32 v26, v26, v2
	v_sub_f32_e32 v10, v10, v2
	v_sub_f32_e32 v27, v27, v2
	v_sub_f32_e32 v11, v11, v2
	v_sub_f32_e32 v28, v28, v2
	v_sub_f32_e32 v12, v12, v2
	v_sub_f32_e32 v29, v29, v2
	v_sub_f32_e32 v13, v13, v2
	v_sub_f32_e32 v30, v30, v2
	v_sub_f32_e32 v14, v14, v2
	v_sub_f32_e32 v31, v31, v2
	v_sub_f32_e32 v15, v15, v2
	v_sub_f32_e32 v32, v32, v2
	v_sub_f32_e32 v16, v16, v2
	v_sub_f32_e32 v33, v33, v2
	v_sub_f32_e32 v17, v17, v2
	v_sub_f32_e32 v34, v34, v2
	v_sub_f32_e32 v18, v18, v2
	v_sub_f32_e32 v35, v35, v2
	v_sub_f32_e32 v2, v19, v2
	v_exp_f32_e32 v114, v20
	v_exp_f32_e32 v115, v21
	v_exp_f32_e32 v116, v22
	v_exp_f32_e32 v117, v23
	v_exp_f32_e32 v118, v24
	v_exp_f32_e32 v119, v25
	v_exp_f32_e32 v120, v26
	v_exp_f32_e32 v121, v27
	v_exp_f32_e32 v122, v28
	v_exp_f32_e32 v123, v29
	v_exp_f32_e32 v124, v30
	v_exp_f32_e32 v125, v31
	v_exp_f32_e32 v126, v32
	v_exp_f32_e32 v127, v33
	v_exp_f32_e32 v128, v34
	v_exp_f32_e32 v129, v35
	v_exp_f32_e32 v98, v4
	v_exp_f32_e32 v99, v5
	v_exp_f32_e32 v100, v6
	v_exp_f32_e32 v101, v7
	v_exp_f32_e32 v102, v8
	v_exp_f32_e32 v103, v9
	v_exp_f32_e32 v104, v10
	v_exp_f32_e32 v105, v11
	v_exp_f32_e32 v106, v12
	v_exp_f32_e32 v107, v13
	v_exp_f32_e32 v108, v14
	v_exp_f32_e32 v109, v15
	v_exp_f32_e32 v110, v16
	v_exp_f32_e32 v111, v17
	v_exp_f32_e32 v112, v18
	v_exp_f32_e32 v113, v2
	s_waitcnt vmcnt(4) lgkmcnt(0)
	s_barrier
	s_cmp_lt_i32 s86, 7
	v_cmp_gt_u32_e64 s[2:3], 32, v233
	s_cbranch_scc1 .LBB0_1083
	v_mov_b32_e32 v16, v3
	v_mov_b32_e32 v17, v3
	v_mov_b32_e32 v2, v3
	v_mov_b32_e32 v4, v3
	v_mov_b32_e32 v5, v3
	v_mov_b32_e32 v6, v3
	v_mov_b32_e32 v7, v3
	v_mov_b32_e32 v8, v3
	v_mov_b32_e32 v9, v3
	v_mov_b32_e32 v10, v3
	v_mov_b32_e32 v11, v3
	v_mov_b32_e32 v12, v3
	v_mov_b32_e32 v13, v3
	v_mov_b32_e32 v14, v3
	v_mov_b32_e32 v15, v3
	v_mov_b64_e32 v[80:81], v[16:17]
	v_mov_b64_e32 v[64:65], v[16:17]
	v_mov_b64_e32 v[48:49], v[16:17]
	v_mov_b64_e32 v[32:33], v[16:17]
	s_mov_b32 s0, 0
	s_mov_b32 s34, 0x8000
	s_movk_i32 s36, 0x4000
	v_mov_b32_e32 v248, 0
	s_mov_b32 s35, 6
	v_mov_b64_e32 v[78:79], v[14:15]
	v_mov_b64_e32 v[76:77], v[12:13]
	v_mov_b64_e32 v[74:75], v[10:11]
	v_mov_b64_e32 v[72:73], v[8:9]
	v_mov_b64_e32 v[70:71], v[6:7]
	v_mov_b64_e32 v[68:69], v[4:5]
	v_mov_b64_e32 v[66:67], v[2:3]
	v_mov_b64_e32 v[62:63], v[14:15]
	v_mov_b64_e32 v[60:61], v[12:13]
	v_mov_b64_e32 v[58:59], v[10:11]
	v_mov_b64_e32 v[56:57], v[8:9]
	v_mov_b64_e32 v[54:55], v[6:7]
	v_mov_b64_e32 v[52:53], v[4:5]
	v_mov_b64_e32 v[50:51], v[2:3]
	v_mov_b64_e32 v[46:47], v[14:15]
	v_mov_b64_e32 v[44:45], v[12:13]
	v_mov_b64_e32 v[42:43], v[10:11]
	v_mov_b64_e32 v[40:41], v[8:9]
	v_mov_b64_e32 v[38:39], v[6:7]
	v_mov_b64_e32 v[36:37], v[4:5]
	v_mov_b64_e32 v[34:35], v[2:3]
	v_mov_b64_e32 v[30:31], v[14:15]
	v_mov_b64_e32 v[28:29], v[12:13]
	v_mov_b64_e32 v[26:27], v[10:11]
	v_mov_b64_e32 v[24:25], v[8:9]
	v_mov_b64_e32 v[22:23], v[6:7]
	v_mov_b64_e32 v[20:21], v[4:5]
	v_mov_b64_e32 v[18:19], v[2:3]
	ds_read_b128 v[210:213], v244
	ds_read_b128 v[214:217], v244 offset:1024
	ds_read_b128 v[218:221], v244 offset:2048
	ds_read_b128 v[222:225], v244 offset:3072
.LBB0_1068:
	v_add_u32_e32 v16, s0, v246
	ds_read_b64_tr_b16 v[6:7], v16 offset:49664
	ds_read_b64_tr_b16 v[4:5], v16 offset:49152
	s_waitcnt lgkmcnt(2)
	v_mfma_f32_32x32x16_bf16 v[146:161], v[206:209], v[210:213], v[82:97]
	v_add_f32_e32 v2, v114, v115
	v_add_f32_e32 v2, v116, v2
	v_add_f32_e32 v2, v117, v2
	v_add_f32_e32 v2, v118, v2
	v_add_f32_e32 v2, v119, v2
	v_cvt_pk_bf16_f32 v174, v114, v115
	v_cvt_pk_bf16_f32 v175, v116, v117
	ds_read_b64_tr_b16 v[10:11], v16 offset:53760
	ds_read_b64_tr_b16 v[8:9], v16 offset:53248
	v_mfma_f32_32x32x16_bf16 v[130:145], v[202:205], v[210:213], v[82:97]
	v_add_f32_e32 v2, v120, v2
	v_add_f32_e32 v2, v121, v2
	v_add_f32_e32 v2, v122, v2
	v_add_f32_e32 v2, v123, v2
	v_cvt_pk_bf16_f32 v176, v118, v119
	v_cvt_pk_bf16_f32 v177, v120, v121
	ds_read_b64_tr_b16 v[12:13], v16 offset:50176
	ds_read_b64_tr_b16 v[14:15], v16 offset:50688
	s_waitcnt lgkmcnt(2)
	v_mfma_f32_32x32x16_bf16 v[146:161], v[198:201], v[214:217], v[146:161]
	v_add_f32_e32 v2, v124, v2
	v_add_f32_e32 v2, v125, v2
	v_add_f32_e32 v2, v126, v2
	v_add_f32_e32 v2, v127, v2
	v_cvt_pk_bf16_f32 v170, v122, v123
	v_cvt_pk_bf16_f32 v171, v124, v125
	ds_read_b64_tr_b16 v[116:117], v16 offset:54784
	ds_read_b64_tr_b16 v[114:115], v16 offset:54272
	v_mfma_f32_32x32x16_bf16 v[130:145], v[194:197], v[214:217], v[130:145]
	v_add_f32_e32 v2, v128, v2
	v_add_f32_e32 v2, v129, v2
	v_add_f32_e32 v2, v98, v2
	v_add_f32_e32 v2, v99, v2
	v_cvt_pk_bf16_f32 v172, v126, v127
	v_cvt_pk_bf16_f32 v173, v128, v129
	ds_read_b64_tr_b16 v[118:119], v16 offset:51200
	ds_read_b64_tr_b16 v[120:121], v16 offset:51712
	s_waitcnt lgkmcnt(2)
	v_mfma_f32_32x32x16_bf16 v[146:161], v[190:193], v[218:221], v[146:161]
	v_add_f32_e32 v2, v100, v2
	v_add_f32_e32 v2, v101, v2
	v_add_f32_e32 v2, v102, v2
	v_add_f32_e32 v2, v103, v2
	v_cvt_pk_bf16_f32 v166, v98, v99
	v_cvt_pk_bf16_f32 v167, v100, v101
	ds_read_b64_tr_b16 v[100:101], v16 offset:55808
	ds_read_b64_tr_b16 v[98:99], v16 offset:55296
	v_mfma_f32_32x32x16_bf16 v[130:145], v[186:189], v[218:221], v[130:145]
	v_add_f32_e32 v2, v104, v2
	v_add_f32_e32 v2, v105, v2
	v_add_f32_e32 v2, v106, v2
	v_add_f32_e32 v2, v107, v2
	v_cvt_pk_bf16_f32 v168, v102, v103
	v_cvt_pk_bf16_f32 v169, v104, v105
	ds_read_b64_tr_b16 v[102:103], v16 offset:52224
	ds_read_b64_tr_b16 v[104:105], v16 offset:52736
	s_waitcnt lgkmcnt(2)
	v_mfma_f32_32x32x16_bf16 v[146:161], v[182:185], v[222:225], v[146:161]
	v_add_f32_e32 v2, v108, v2
	v_add_f32_e32 v2, v109, v2
	v_add_f32_e32 v2, v110, v2
	v_add_f32_e32 v2, v111, v2
	v_cvt_pk_bf16_f32 v162, v106, v107
	v_cvt_pk_bf16_f32 v163, v108, v109
	ds_read_b64_tr_b16 v[106:107], v16 offset:56320
	ds_read_b64_tr_b16 v[108:109], v16 offset:56832
	v_mfma_f32_32x32x16_bf16 v[130:145], v[178:181], v[222:225], v[130:145]
	v_add_f32_e32 v2, v112, v2
	v_add_f32_e32 v2, v113, v2
	v_add_f32_e32 v2, 0, v2
	v_cvt_pk_bf16_f32 v164, v110, v111
	v_cvt_pk_bf16_f32 v165, v112, v113
	s_add_i32 s0, s35, -2
	v_max_f32_e32 v17, v147, v147
	v_max_f32_e32 v110, v146, v146
	s_min_i32 s0, s0, s91
	v_max_f32_e32 v17, v110, v17
	s_ashr_i32 s1, s0, 31
	s_nop 0
	v_max3_f32 v110, v148, v149, v131
	v_max3_f32 v17, v17, v130, v132
	s_lshl_b64 s[0:1], s[0:1], 17
	v_max3_f32 v17, v17, v133, v150
	v_max3_f32 v110, v110, v152, v153
	s_add_u32 s0, s87, s0
	v_max3_f32 v17, v17, v151, v134
	v_max3_f32 v110, v110, v136, v137
	s_addc_u32 s1, s88, s1
	s_add_i32 s4, s36, s81
	v_max3_f32 v17, v17, v135, v154
	v_max3_f32 v110, v110, v156, v157
	s_mov_b32 s5, m0
	s_mov_b32 m0, s4
	s_nop 4
	global_load_lds_dwordx4 v237, s[0:1]
	s_mov_b32 m0, s5
	s_add_u32 s0, s0, 0x80
	v_max3_f32 v17, v17, v155, v138
	v_max3_f32 v110, v110, v140, v141
	s_addc_u32 s1, s1, 0
	s_add_i32 s4, s36, s82
	s_mov_b32 s5, m0
	s_mov_b32 m0, s4
	s_nop 4
	global_load_lds_dwordx4 v237, s[0:1]
	s_mov_b32 m0, s5
	s_add_i32 s0, s35, -4
	v_max3_f32 v17, v17, v139, v158
	v_max3_f32 v110, v110, v160, v161
	s_min_i32 s0, s0, s91
	v_max3_f32 v17, v17, v159, v142
	v_max3_f32 v110, v110, v144, v145
	s_ashr_i32 s1, s0, 31
	v_max3_f32 v17, v17, v143, v110
	s_lshl_b64 s[0:1], s[0:1], 17
	v_mov_b32_e32 v110, v17
	s_add_u32 s0, s89, s0
	s_nop 0
	v_permlane32_swap_b32_e32 v17, v110
	s_addc_u32 s1, s90, s1
	s_add_i32 s4, s34, s80
	v_max_f32_e32 v110, v110, v110
	v_max_f32_e32 v17, v17, v17
	s_mov_b32 s5, m0
	s_mov_b32 m0, s4
	s_nop 4
	global_load_lds_dwordx4 v238, s[0:1]
	s_mov_b32 m0, s5
	s_add_u32 s0, s0, 0x80
	v_max_f32_e32 v17, v17, v110
	s_addc_u32 s1, s1, 0
	s_add_i32 s4, s34, s84
	s_mov_b32 s5, m0
	s_mov_b32 m0, s4
	s_nop 4
	global_load_lds_dwordx4 v238, s[0:1]
	s_mov_b32 m0, s5
	v_cmp_lt_f32_e32 vcc, s62, v17
	s_cmp_lg_u64 vcc, 0
	v_add_f32_e32 v2, v248, v2
	s_cselect_b64 s[0:1], -1, 0
	s_cbranch_vccnz .LBB0_1076

.LBB0_1071:
	s_add_i32 s0, s34, 0x4000
	s_cmpk_lg_u32 s34, 0x8000
	s_cselect_b32 s92, s0, 0
	v_add_u32_e32 v16, s36, v246
	ds_read_b64_tr_b16 v[180:181], v16 offset:49664
	ds_read_b64_tr_b16 v[178:179], v16 offset:49152
	s_waitcnt lgkmcnt(2)
	v_mfma_f32_32x32x16_bf16 v[114:129], v[98:101], v[210:213], v[82:97]
	v_add_f32_e32 v17, v146, v147
	v_add_f32_e32 v17, v148, v17
	v_add_f32_e32 v17, v149, v17
	v_add_f32_e32 v17, v150, v17
	v_add_f32_e32 v17, v151, v17
	v_cvt_pk_bf16_f32 v174, v146, v147
	v_cvt_pk_bf16_f32 v175, v148, v149
	ds_read_b64_tr_b16 v[148:149], v16 offset:53760
	ds_read_b64_tr_b16 v[146:147], v16 offset:53248
	v_mfma_f32_32x32x16_bf16 v[98:113], v[194:197], v[210:213], v[82:97]
	v_add_f32_e32 v17, v152, v17
	v_add_f32_e32 v17, v153, v17
	v_add_f32_e32 v17, v154, v17
	v_add_f32_e32 v17, v155, v17
	v_cvt_pk_bf16_f32 v176, v150, v151
	v_cvt_pk_bf16_f32 v177, v152, v153
	ds_read_b64_tr_b16 v[150:151], v16 offset:50176
	ds_read_b64_tr_b16 v[152:153], v16 offset:50688
	s_waitcnt lgkmcnt(2)
	v_mfma_f32_32x32x16_bf16 v[114:129], v[190:193], v[214:217], v[114:129]
	v_add_f32_e32 v17, v156, v17
	v_add_f32_e32 v17, v157, v17
	v_add_f32_e32 v17, v158, v17
	v_add_f32_e32 v17, v159, v17
	v_cvt_pk_bf16_f32 v170, v154, v155
	v_cvt_pk_bf16_f32 v171, v156, v157
	ds_read_b64_tr_b16 v[156:157], v16 offset:54784
	ds_read_b64_tr_b16 v[154:155], v16 offset:54272
	v_mfma_f32_32x32x16_bf16 v[98:113], v[186:189], v[214:217], v[98:113]
	v_add_f32_e32 v17, v160, v17
	v_add_f32_e32 v17, v161, v17
	v_add_f32_e32 v17, v130, v17
	v_add_f32_e32 v17, v131, v17
	v_cvt_pk_bf16_f32 v172, v158, v159
	v_cvt_pk_bf16_f32 v173, v160, v161
	ds_read_b64_tr_b16 v[158:159], v16 offset:51200
	ds_read_b64_tr_b16 v[160:161], v16 offset:51712
	s_waitcnt lgkmcnt(2)
	v_mfma_f32_32x32x16_bf16 v[114:129], v[182:185], v[218:221], v[114:129]
	v_add_f32_e32 v17, v132, v17
	v_add_f32_e32 v17, v133, v17
	v_add_f32_e32 v17, v134, v17
	v_add_f32_e32 v17, v135, v17
	v_cvt_pk_bf16_f32 v166, v130, v131
	v_cvt_pk_bf16_f32 v167, v132, v133
	ds_read_b64_tr_b16 v[132:133], v16 offset:55808
	ds_read_b64_tr_b16 v[130:131], v16 offset:55296
	v_mfma_f32_32x32x16_bf16 v[98:113], v[12:15], v[218:221], v[98:113]
	v_add_f32_e32 v17, v136, v17
	v_add_f32_e32 v17, v137, v17
	v_add_f32_e32 v17, v138, v17
	v_add_f32_e32 v17, v139, v17
	v_cvt_pk_bf16_f32 v168, v134, v135
	v_cvt_pk_bf16_f32 v169, v136, v137
	ds_read_b64_tr_b16 v[12:13], v16 offset:52224
	ds_read_b64_tr_b16 v[14:15], v16 offset:52736
	s_waitcnt lgkmcnt(2)
	v_mfma_f32_32x32x16_bf16 v[114:129], v[8:11], v[222:225], v[114:129]
	v_add_f32_e32 v17, v140, v17
	v_add_f32_e32 v17, v141, v17
	v_add_f32_e32 v17, v142, v17
	v_add_f32_e32 v17, v143, v17
	v_cvt_pk_bf16_f32 v162, v138, v139
	v_cvt_pk_bf16_f32 v163, v140, v141
	ds_read_b64_tr_b16 v[8:9], v16 offset:56320
	ds_read_b64_tr_b16 v[10:11], v16 offset:56832
	v_mfma_f32_32x32x16_bf16 v[98:113], v[4:7], v[222:225], v[98:113]
	v_add_f32_e32 v17, v144, v17
	v_add_f32_e32 v17, v145, v17
	v_add_f32_e32 v17, 0, v17
	v_cvt_pk_bf16_f32 v164, v142, v143
	v_cvt_pk_bf16_f32 v165, v144, v145
	s_add_i32 s0, s35, -1
	v_max_f32_e32 v4, v115, v115
	v_max_f32_e32 v5, v114, v114
	s_min_i32 s0, s0, s91
	v_max_f32_e32 v4, v5, v4
	s_ashr_i32 s1, s0, 31
	s_nop 0
	v_max3_f32 v5, v116, v117, v99
	v_max3_f32 v4, v4, v98, v100
	s_lshl_b64 s[0:1], s[0:1], 17
	v_max3_f32 v4, v4, v101, v118
	v_max3_f32 v5, v5, v120, v121
	s_add_u32 s0, s87, s0
	v_max3_f32 v4, v4, v119, v102
	v_max3_f32 v5, v5, v104, v105
	s_addc_u32 s1, s88, s1
	s_add_i32 s4, s34, s81
	v_max3_f32 v4, v4, v103, v122
	v_max3_f32 v5, v5, v124, v125
	s_mov_b32 s5, m0
	s_mov_b32 m0, s4
	s_nop 4
	global_load_lds_dwordx4 v237, s[0:1]
	s_mov_b32 m0, s5
	s_add_u32 s0, s0, 0x80
	v_max3_f32 v4, v4, v123, v106
	v_max3_f32 v5, v5, v108, v109
	s_addc_u32 s1, s1, 0
	s_add_i32 s93, s35, -3
	v_max3_f32 v4, v4, v107, v126
	v_max3_f32 v5, v5, v128, v129
	s_add_i32 s4, s34, s82
	s_mov_b32 s5, m0
	s_mov_b32 m0, s4
	s_nop 4
	global_load_lds_dwordx4 v237, s[0:1]
	s_mov_b32 m0, s5
	s_min_i32 s0, s93, s91
	v_max3_f32 v4, v4, v127, v110
	v_max3_f32 v5, v5, v112, v113
	s_ashr_i32 s1, s0, 31
	v_add_f32_e32 v248, v2, v17
	v_max3_f32 v2, v4, v111, v5
	s_lshl_b64 s[0:1], s[0:1], 17
	v_mov_b32_e32 v4, v2
	s_add_u32 s0, s89, s0
	s_nop 0
	v_permlane32_swap_b32_e32 v2, v4
	s_addc_u32 s1, s90, s1
	s_add_i32 s4, s92, s80
	v_max_f32_e32 v4, v4, v4
	v_max_f32_e32 v2, v2, v2
	s_mov_b32 s5, m0
	s_mov_b32 m0, s4
	s_nop 4
	global_load_lds_dwordx4 v238, s[0:1]
	s_mov_b32 m0, s5
	s_add_u32 s0, s0, 0x80
	v_max_f32_e32 v2, v2, v4
	s_addc_u32 s1, s1, 0
	s_add_i32 s4, s92, s84
	s_mov_b32 s5, m0
	s_mov_b32 m0, s4
	s_nop 4
	global_load_lds_dwordx4 v238, s[0:1]
	s_mov_b32 m0, s5
	v_cmp_lt_f32_e32 vcc, s62, v2
	s_cmp_lg_u64 vcc, 0
	s_cselect_b64 s[0:1], -1, 0
	s_cbranch_vccnz .LBB0_1079
